# in_proj PXA tile stores with nt hint (re-test on the current base), on top of the nt ninth-round conversion stream
# baseline (speedup 1.0000x reference)
.LBB0_348:
	s_cmp_lt_i32 s87, 3
	s_cbranch_scc1 .Lpxa_gen_a
	s_add_i32 s0, s87, -9
	s_cmp_lt_u32 s0, 2
	s_cbranch_scc1 .Lpxa_gen_a
	s_lshl_b32 s0, s88, 8
	s_add_i32 s0, s0, s42
	v_or_b32_e32 v202, s0, v204
	s_lshl_b32 s10, s87, 8
	s_mov_b32 s11, 0
	v_lshl_add_u64 v[198:199], s[10:11], 1, v[188:189]
	v_mov_b32_e32 v203, 0
	v_lshlrev_b64 v[18:19], 13, v[202:203]
	v_lshl_add_u64 v[22:23], v[198:199], 0, v[18:19]
	v_cvt_pk_bf16_f32 v0, v162, v163
	v_cvt_pk_bf16_f32 v1, v164, v165
	v_cvt_pk_bf16_f32 v2, v158, v159
	v_cvt_pk_bf16_f32 v3, v160, v161
	global_store_dwordx4 v[22:23], v[0:3], off nt
	v_cvt_pk_bf16_f32 v4, v154, v155
	v_cvt_pk_bf16_f32 v5, v156, v157
	v_cvt_pk_bf16_f32 v6, v150, v151
	v_cvt_pk_bf16_f32 v7, v152, v153
	global_store_dwordx4 v[22:23], v[4:7], off offset:256 nt
	s_mov_b32 s8, 0x20000
	s_mov_b32 s9, 0
	v_lshl_add_u64 v[26:27], v[22:23], 0, s[8:9]
	v_cvt_pk_bf16_f32 v8, v146, v147
	v_cvt_pk_bf16_f32 v9, v148, v149
	v_cvt_pk_bf16_f32 v10, v142, v143
	v_cvt_pk_bf16_f32 v11, v144, v145
	global_store_dwordx4 v[26:27], v[8:11], off nt
	v_cvt_pk_bf16_f32 v12, v138, v139
	v_cvt_pk_bf16_f32 v13, v140, v141
	v_cvt_pk_bf16_f32 v14, v134, v135
	v_cvt_pk_bf16_f32 v15, v136, v137
	global_store_dwordx4 v[26:27], v[12:15], off offset:256 nt
	s_mov_b32 s8, 0x40000
	s_mov_b32 s9, 0
	v_lshl_add_u64 v[28:29], v[22:23], 0, s[8:9]
	v_cvt_pk_bf16_f32 v0, v130, v131
	v_cvt_pk_bf16_f32 v1, v132, v133
	v_cvt_pk_bf16_f32 v2, v126, v127
	v_cvt_pk_bf16_f32 v3, v128, v129
	global_store_dwordx4 v[28:29], v[0:3], off nt
	v_cvt_pk_bf16_f32 v4, v122, v123
	v_cvt_pk_bf16_f32 v5, v124, v125
	v_cvt_pk_bf16_f32 v6, v118, v119
	v_cvt_pk_bf16_f32 v7, v120, v121
	global_store_dwordx4 v[28:29], v[4:7], off offset:256 nt
	s_mov_b32 s8, 0x60000
	s_mov_b32 s9, 0
	v_lshl_add_u64 v[24:25], v[22:23], 0, s[8:9]
	v_cvt_pk_bf16_f32 v8, v114, v115
	v_cvt_pk_bf16_f32 v9, v116, v117
	v_cvt_pk_bf16_f32 v10, v110, v111
	v_cvt_pk_bf16_f32 v11, v112, v113
	global_store_dwordx4 v[24:25], v[8:11], off nt
	v_cvt_pk_bf16_f32 v12, v106, v107
	v_cvt_pk_bf16_f32 v13, v108, v109
	v_cvt_pk_bf16_f32 v14, v102, v103
	v_cvt_pk_bf16_f32 v15, v104, v105
	global_store_dwordx4 v[24:25], v[12:15], off offset:256 nt
	s_mov_b32 s8, 0x100000
	s_mov_b32 s9, 0
	v_lshl_add_u64 v[26:27], v[22:23], 0, s[8:9]
	v_cvt_pk_bf16_f32 v0, v98, v99
	v_cvt_pk_bf16_f32 v1, v100, v101
	v_cvt_pk_bf16_f32 v2, v94, v95
	v_cvt_pk_bf16_f32 v3, v96, v97
	global_store_dwordx4 v[26:27], v[0:3], off nt
	v_cvt_pk_bf16_f32 v4, v90, v91
	v_cvt_pk_bf16_f32 v5, v92, v93
	v_cvt_pk_bf16_f32 v6, v86, v87
	v_cvt_pk_bf16_f32 v7, v88, v89
	global_store_dwordx4 v[26:27], v[4:7], off offset:256 nt
	s_mov_b32 s8, 0x120000
	s_mov_b32 s9, 0
	v_lshl_add_u64 v[28:29], v[22:23], 0, s[8:9]
	v_cvt_pk_bf16_f32 v8, v82, v83
	v_cvt_pk_bf16_f32 v9, v84, v85
	v_cvt_pk_bf16_f32 v10, v78, v79
	v_cvt_pk_bf16_f32 v11, v80, v81
	global_store_dwordx4 v[28:29], v[8:11], off nt
	v_cvt_pk_bf16_f32 v12, v74, v75
	v_cvt_pk_bf16_f32 v13, v76, v77
	v_cvt_pk_bf16_f32 v14, v70, v71
	v_cvt_pk_bf16_f32 v15, v72, v73
	global_store_dwordx4 v[28:29], v[12:15], off offset:256 nt
	s_mov_b32 s8, 0x140000
	s_mov_b32 s9, 0
	v_lshl_add_u64 v[24:25], v[22:23], 0, s[8:9]
	v_cvt_pk_bf16_f32 v0, v66, v67
	v_cvt_pk_bf16_f32 v1, v68, v69
	v_cvt_pk_bf16_f32 v2, v62, v63
	v_cvt_pk_bf16_f32 v3, v64, v65
	global_store_dwordx4 v[24:25], v[0:3], off nt
	v_cvt_pk_bf16_f32 v4, v58, v59
	v_cvt_pk_bf16_f32 v5, v60, v61
	v_cvt_pk_bf16_f32 v6, v54, v55
	v_cvt_pk_bf16_f32 v7, v56, v57
	global_store_dwordx4 v[24:25], v[4:7], off offset:256 nt
	s_mov_b32 s8, 0x160000
	s_mov_b32 s9, 0
	v_lshl_add_u64 v[26:27], v[22:23], 0, s[8:9]
	v_cvt_pk_bf16_f32 v8, v50, v51
	v_cvt_pk_bf16_f32 v9, v52, v53
	v_cvt_pk_bf16_f32 v10, v46, v47
	v_cvt_pk_bf16_f32 v11, v48, v49
	global_store_dwordx4 v[26:27], v[8:11], off nt
	v_cvt_pk_bf16_f32 v12, v42, v43
	v_cvt_pk_bf16_f32 v13, v44, v45
	v_cvt_pk_bf16_f32 v14, v38, v39
	v_cvt_pk_bf16_f32 v15, v40, v41
	global_store_dwordx4 v[26:27], v[12:15], off offset:256 nt
	s_branch .LBB0_366

.LBB0_357:
	s_cmp_eq_u32 s87, 10
	s_cselect_b64 vcc, -1, 0
	v_cndmask_b32_e32 v17, 1.0, v224, vcc
	v_mov_b32_e32 v18, 0x3e38aa3b
	v_cndmask_b32_e64 v196, v17, v18, s[10:11]
	s_lshl_b32 s10, s87, 8
	v_or_b32_e32 v202, s0, v204
	s_ashr_i32 s11, s10, 31
	v_ashrrev_i32_e32 v203, 31, v202
	v_lshl_add_u64 v[198:199], s[10:11], 1, v[188:189]
	v_lshlrev_b64 v[18:19], 13, v[202:203]
	v_lshl_add_u64 v[22:23], v[198:199], 0, v[18:19]
	v_pk_mul_f32 v[18:19], v[160:161], v[2:3]
	v_pk_mul_f32 v[20:21], v[158:159], v[0:1]
	v_pk_mul_f32 v[24:25], v[160:161], v[180:181]
	v_pk_mul_f32 v[26:27], v[158:159], v[178:179]
	v_pk_fma_f32 v[18:19], v[164:165], v[180:181], v[18:19] neg_lo:[0,0,1] neg_hi:[0,0,1]
	v_pk_fma_f32 v[20:21], v[162:163], v[178:179], v[20:21] neg_lo:[0,0,1] neg_hi:[0,0,1]
	v_pk_fma_f32 v[24:25], v[164:165], v[2:3], v[24:25]
	v_pk_fma_f32 v[26:27], v[162:163], v[0:1], v[26:27]
	v_cndmask_b32_e64 v19, v165, v19, s[8:9]
	v_cndmask_b32_e64 v18, v164, v18, s[8:9]
	v_cndmask_b32_e64 v21, v163, v21, s[8:9]
	v_cndmask_b32_e64 v20, v162, v20, s[8:9]
	v_cndmask_b32_e64 v25, v161, v25, s[8:9]
	v_cndmask_b32_e64 v24, v160, v24, s[8:9]
	v_cndmask_b32_e64 v27, v159, v27, s[8:9]
	v_cndmask_b32_e64 v26, v158, v26, s[8:9]
	v_pk_mul_f32 v[28:29], v[196:197], v[18:19] op_sel_hi:[0,1]
	v_pk_mul_f32 v[18:19], v[196:197], v[20:21] op_sel_hi:[0,1]
	v_pk_mul_f32 v[24:25], v[196:197], v[24:25] op_sel_hi:[0,1]
	v_pk_mul_f32 v[20:21], v[196:197], v[26:27] op_sel_hi:[0,1]
	v_cvt_pk_bf16_f32 v18, v18, v19
	v_cvt_pk_bf16_f32 v19, v28, v29
	v_cvt_pk_bf16_f32 v20, v20, v21
	v_cvt_pk_bf16_f32 v21, v24, v25
	global_store_dwordx4 v[22:23], v[18:21], off nt
	v_pk_mul_f32 v[24:25], v[152:153], v[180:181]
	v_pk_mul_f32 v[26:27], v[150:151], v[178:179]
	v_pk_mul_f32 v[18:19], v[152:153], v[2:3]
	v_pk_mul_f32 v[20:21], v[150:151], v[0:1]
	v_pk_fma_f32 v[18:19], v[156:157], v[180:181], v[18:19] neg_lo:[0,0,1] neg_hi:[0,0,1]
	v_pk_fma_f32 v[20:21], v[154:155], v[178:179], v[20:21] neg_lo:[0,0,1] neg_hi:[0,0,1]
	v_pk_fma_f32 v[2:3], v[156:157], v[2:3], v[24:25]
	v_pk_fma_f32 v[0:1], v[154:155], v[0:1], v[26:27]
	s_and_b64 s[10:11], s[74:75], s[34:35]
	v_cndmask_b32_e64 v21, v155, v21, s[10:11]
	v_cndmask_b32_e64 v20, v154, v20, s[10:11]
	v_cndmask_b32_e64 v19, v157, v19, s[10:11]
	v_cndmask_b32_e64 v18, v156, v18, s[10:11]
	v_cndmask_b32_e64 v1, v151, v1, s[10:11]
	v_cndmask_b32_e64 v0, v150, v0, s[10:11]
	v_cndmask_b32_e64 v3, v153, v3, s[10:11]
	v_cndmask_b32_e64 v2, v152, v2, s[10:11]
	v_pk_mul_f32 v[18:19], v[196:197], v[18:19] op_sel_hi:[0,1]
	v_pk_mul_f32 v[20:21], v[196:197], v[20:21] op_sel_hi:[0,1]
	v_pk_mul_f32 v[24:25], v[196:197], v[2:3] op_sel_hi:[0,1]
	v_pk_mul_f32 v[2:3], v[196:197], v[0:1] op_sel_hi:[0,1]
	v_cvt_pk_bf16_f32 v0, v20, v21
	v_cvt_pk_bf16_f32 v1, v18, v19
	v_cvt_pk_bf16_f32 v2, v2, v3
	v_cvt_pk_bf16_f32 v3, v24, v25
	global_store_dwordx4 v[22:23], v[0:3], off offset:256 nt
	v_pk_mul_f32 v[20:21], v[144:145], v[176:177]
	v_pk_mul_f32 v[22:23], v[142:143], v[174:175]
	v_or_b32_e32 v0, 16, v202
	v_ashrrev_i32_e32 v1, 31, v0
	v_lshlrev_b64 v[0:1], 13, v[0:1]
	v_lshl_add_u64 v[18:19], v[198:199], 0, v[0:1]
	v_pk_mul_f32 v[0:1], v[144:145], v[6:7]
	v_pk_mul_f32 v[2:3], v[142:143], v[4:5]
	v_pk_fma_f32 v[0:1], v[148:149], v[176:177], v[0:1] neg_lo:[0,0,1] neg_hi:[0,0,1]
	v_pk_fma_f32 v[2:3], v[146:147], v[174:175], v[2:3] neg_lo:[0,0,1] neg_hi:[0,0,1]
	v_pk_fma_f32 v[20:21], v[148:149], v[6:7], v[20:21]
	v_pk_fma_f32 v[22:23], v[146:147], v[4:5], v[22:23]
	v_cndmask_b32_e64 v3, v147, v3, s[8:9]
	v_cndmask_b32_e64 v2, v146, v2, s[8:9]
	v_cndmask_b32_e64 v1, v149, v1, s[8:9]
	v_cndmask_b32_e64 v0, v148, v0, s[8:9]
	v_cndmask_b32_e64 v23, v143, v23, s[8:9]
	v_cndmask_b32_e64 v22, v142, v22, s[8:9]
	v_cndmask_b32_e64 v21, v145, v21, s[8:9]
	v_cndmask_b32_e64 v20, v144, v20, s[8:9]
	v_pk_mul_f32 v[24:25], v[196:197], v[0:1] op_sel_hi:[0,1]
	v_pk_mul_f32 v[0:1], v[196:197], v[2:3] op_sel_hi:[0,1]
	v_pk_mul_f32 v[20:21], v[196:197], v[20:21] op_sel_hi:[0,1]
	v_pk_mul_f32 v[2:3], v[196:197], v[22:23] op_sel_hi:[0,1]
	v_cvt_pk_bf16_f32 v0, v0, v1
	v_cvt_pk_bf16_f32 v1, v24, v25
	v_cvt_pk_bf16_f32 v2, v2, v3
	v_cvt_pk_bf16_f32 v3, v20, v21
	global_store_dwordx4 v[18:19], v[0:3], off nt
	v_pk_mul_f32 v[20:21], v[136:137], v[176:177]
	v_pk_mul_f32 v[22:23], v[134:135], v[174:175]
	v_pk_mul_f32 v[0:1], v[136:137], v[6:7]
	v_pk_mul_f32 v[2:3], v[134:135], v[4:5]
	v_pk_fma_f32 v[0:1], v[140:141], v[176:177], v[0:1] neg_lo:[0,0,1] neg_hi:[0,0,1]
	v_pk_fma_f32 v[2:3], v[138:139], v[174:175], v[2:3] neg_lo:[0,0,1] neg_hi:[0,0,1]
	v_pk_fma_f32 v[6:7], v[140:141], v[6:7], v[20:21]
	v_pk_fma_f32 v[4:5], v[138:139], v[4:5], v[22:23]
	v_cndmask_b32_e64 v3, v139, v3, s[10:11]
	v_cndmask_b32_e64 v2, v138, v2, s[10:11]
	v_cndmask_b32_e64 v1, v141, v1, s[10:11]
	v_cndmask_b32_e64 v0, v140, v0, s[10:11]
	v_cndmask_b32_e64 v5, v135, v5, s[10:11]
	v_cndmask_b32_e64 v4, v134, v4, s[10:11]
	v_cndmask_b32_e64 v7, v137, v7, s[10:11]
	v_cndmask_b32_e64 v6, v136, v6, s[10:11]
	v_pk_mul_f32 v[20:21], v[196:197], v[0:1] op_sel_hi:[0,1]
	v_pk_mul_f32 v[0:1], v[196:197], v[2:3] op_sel_hi:[0,1]
	v_pk_mul_f32 v[6:7], v[196:197], v[6:7] op_sel_hi:[0,1]
	v_pk_mul_f32 v[2:3], v[196:197], v[4:5] op_sel_hi:[0,1]
	v_cvt_pk_bf16_f32 v0, v0, v1
	v_cvt_pk_bf16_f32 v1, v20, v21
	v_cvt_pk_bf16_f32 v2, v2, v3
	v_cvt_pk_bf16_f32 v3, v6, v7
	global_store_dwordx4 v[18:19], v[0:3], off offset:256 nt
	s_waitcnt vmcnt(4)
	v_pk_mul_f32 v[6:7], v[128:129], v[172:173]
	v_pk_mul_f32 v[18:19], v[126:127], v[170:171]
	v_or_b32_e32 v0, 32, v202
	v_ashrrev_i32_e32 v1, 31, v0
	v_lshlrev_b64 v[0:1], 13, v[0:1]
	v_lshl_add_u64 v[4:5], v[198:199], 0, v[0:1]
	v_pk_mul_f32 v[0:1], v[128:129], v[10:11]
	v_pk_mul_f32 v[2:3], v[126:127], v[8:9]
	v_pk_fma_f32 v[0:1], v[132:133], v[172:173], v[0:1] neg_lo:[0,0,1] neg_hi:[0,0,1]
	v_pk_fma_f32 v[2:3], v[130:131], v[170:171], v[2:3] neg_lo:[0,0,1] neg_hi:[0,0,1]
	v_pk_fma_f32 v[6:7], v[132:133], v[10:11], v[6:7]
	v_pk_fma_f32 v[18:19], v[130:131], v[8:9], v[18:19]
	v_cndmask_b32_e64 v3, v131, v3, s[8:9]
	v_cndmask_b32_e64 v2, v130, v2, s[8:9]
	v_cndmask_b32_e64 v1, v133, v1, s[8:9]
	v_cndmask_b32_e64 v0, v132, v0, s[8:9]
	v_cndmask_b32_e64 v19, v127, v19, s[8:9]
	v_cndmask_b32_e64 v18, v126, v18, s[8:9]
	v_cndmask_b32_e64 v7, v129, v7, s[8:9]
	v_cndmask_b32_e64 v6, v128, v6, s[8:9]
	v_pk_mul_f32 v[20:21], v[196:197], v[0:1] op_sel_hi:[0,1]
	v_pk_mul_f32 v[0:1], v[196:197], v[2:3] op_sel_hi:[0,1]
	v_pk_mul_f32 v[6:7], v[196:197], v[6:7] op_sel_hi:[0,1]
	v_pk_mul_f32 v[2:3], v[196:197], v[18:19] op_sel_hi:[0,1]
	v_cvt_pk_bf16_f32 v0, v0, v1
	v_cvt_pk_bf16_f32 v1, v20, v21
	v_cvt_pk_bf16_f32 v2, v2, v3
	v_cvt_pk_bf16_f32 v3, v6, v7
	global_store_dwordx4 v[4:5], v[0:3], off nt
	v_pk_mul_f32 v[6:7], v[120:121], v[172:173]
	v_pk_mul_f32 v[18:19], v[118:119], v[170:171]
	v_pk_mul_f32 v[0:1], v[120:121], v[10:11]
	v_pk_mul_f32 v[2:3], v[118:119], v[8:9]
	v_pk_fma_f32 v[0:1], v[124:125], v[172:173], v[0:1] neg_lo:[0,0,1] neg_hi:[0,0,1]
	v_pk_fma_f32 v[2:3], v[122:123], v[170:171], v[2:3] neg_lo:[0,0,1] neg_hi:[0,0,1]
	v_pk_fma_f32 v[6:7], v[124:125], v[10:11], v[6:7]
	v_pk_fma_f32 v[8:9], v[122:123], v[8:9], v[18:19]
	v_cndmask_b32_e64 v3, v123, v3, s[10:11]
	v_cndmask_b32_e64 v2, v122, v2, s[10:11]
	v_cndmask_b32_e64 v1, v125, v1, s[10:11]
	v_cndmask_b32_e64 v0, v124, v0, s[10:11]
	v_cndmask_b32_e64 v9, v119, v9, s[10:11]
	v_cndmask_b32_e64 v8, v118, v8, s[10:11]
	v_cndmask_b32_e64 v7, v121, v7, s[10:11]
	v_cndmask_b32_e64 v6, v120, v6, s[10:11]
	v_pk_mul_f32 v[10:11], v[196:197], v[0:1] op_sel_hi:[0,1]
	v_pk_mul_f32 v[0:1], v[196:197], v[2:3] op_sel_hi:[0,1]
	v_pk_mul_f32 v[6:7], v[196:197], v[6:7] op_sel_hi:[0,1]
	v_pk_mul_f32 v[2:3], v[196:197], v[8:9] op_sel_hi:[0,1]
	v_cvt_pk_bf16_f32 v0, v0, v1
	v_cvt_pk_bf16_f32 v1, v10, v11
	v_cvt_pk_bf16_f32 v2, v2, v3
	v_cvt_pk_bf16_f32 v3, v6, v7
	global_store_dwordx4 v[4:5], v[0:3], off offset:256 nt
	v_pk_mul_f32 v[6:7], v[112:113], v[168:169]
	v_pk_mul_f32 v[8:9], v[110:111], v[166:167]
	v_or_b32_e32 v0, 48, v202
	v_ashrrev_i32_e32 v1, 31, v0
	v_lshlrev_b64 v[0:1], 13, v[0:1]
	v_lshl_add_u64 v[4:5], v[198:199], 0, v[0:1]
	v_pk_mul_f32 v[0:1], v[112:113], v[14:15]
	v_pk_mul_f32 v[2:3], v[110:111], v[12:13]
	v_pk_fma_f32 v[0:1], v[116:117], v[168:169], v[0:1] neg_lo:[0,0,1] neg_hi:[0,0,1]
	v_pk_fma_f32 v[2:3], v[114:115], v[166:167], v[2:3] neg_lo:[0,0,1] neg_hi:[0,0,1]
	v_pk_fma_f32 v[6:7], v[116:117], v[14:15], v[6:7]
	v_pk_fma_f32 v[8:9], v[114:115], v[12:13], v[8:9]
	v_cndmask_b32_e64 v3, v115, v3, s[8:9]
	v_cndmask_b32_e64 v2, v114, v2, s[8:9]
	v_cndmask_b32_e64 v1, v117, v1, s[8:9]
	v_cndmask_b32_e64 v0, v116, v0, s[8:9]
	v_cndmask_b32_e64 v9, v111, v9, s[8:9]
	v_cndmask_b32_e64 v8, v110, v8, s[8:9]
	v_cndmask_b32_e64 v7, v113, v7, s[8:9]
	v_cndmask_b32_e64 v6, v112, v6, s[8:9]
	v_pk_mul_f32 v[10:11], v[196:197], v[0:1] op_sel_hi:[0,1]
	v_pk_mul_f32 v[0:1], v[196:197], v[2:3] op_sel_hi:[0,1]
	v_pk_mul_f32 v[6:7], v[196:197], v[6:7] op_sel_hi:[0,1]
	v_pk_mul_f32 v[2:3], v[196:197], v[8:9] op_sel_hi:[0,1]
	v_cvt_pk_bf16_f32 v0, v0, v1
	v_cvt_pk_bf16_f32 v1, v10, v11
	v_cvt_pk_bf16_f32 v2, v2, v3
	v_cvt_pk_bf16_f32 v3, v6, v7
	global_store_dwordx4 v[4:5], v[0:3], off nt
	v_pk_mul_f32 v[6:7], v[104:105], v[168:169]
	v_pk_mul_f32 v[8:9], v[102:103], v[166:167]
	v_pk_mul_f32 v[0:1], v[104:105], v[14:15]
	v_pk_mul_f32 v[2:3], v[102:103], v[12:13]
	v_pk_fma_f32 v[0:1], v[108:109], v[168:169], v[0:1] neg_lo:[0,0,1] neg_hi:[0,0,1]
	v_pk_fma_f32 v[2:3], v[106:107], v[166:167], v[2:3] neg_lo:[0,0,1] neg_hi:[0,0,1]
	v_pk_fma_f32 v[6:7], v[108:109], v[14:15], v[6:7]
	v_pk_fma_f32 v[8:9], v[106:107], v[12:13], v[8:9]
	v_cndmask_b32_e64 v3, v107, v3, s[10:11]
	v_cndmask_b32_e64 v2, v106, v2, s[10:11]
	v_cndmask_b32_e64 v1, v109, v1, s[10:11]
	v_cndmask_b32_e64 v0, v108, v0, s[10:11]
	v_cndmask_b32_e64 v9, v103, v9, s[10:11]
	v_cndmask_b32_e64 v8, v102, v8, s[10:11]
	v_cndmask_b32_e64 v7, v105, v7, s[10:11]
	v_cndmask_b32_e64 v6, v104, v6, s[10:11]
	v_pk_mul_f32 v[10:11], v[196:197], v[0:1] op_sel_hi:[0,1]
	v_pk_mul_f32 v[0:1], v[196:197], v[2:3] op_sel_hi:[0,1]
	v_pk_mul_f32 v[6:7], v[196:197], v[6:7] op_sel_hi:[0,1]
	v_pk_mul_f32 v[2:3], v[196:197], v[8:9] op_sel_hi:[0,1]
	s_addk_i32 s0, 0x80
	v_mov_b32_e32 v16, 1.0
	v_cvt_pk_bf16_f32 v0, v0, v1
	v_cvt_pk_bf16_f32 v1, v10, v11
	v_cvt_pk_bf16_f32 v2, v2, v3
	v_cvt_pk_bf16_f32 v3, v6, v7
	s_bfe_u32 s0, s0, 0x60006
	v_mov_b32_e32 v8, 0
	s_and_b64 vcc, exec, s[12:13]
	v_mov_b32_e32 v24, 0
	v_mov_b32_e32 v25, 0
	v_mov_b32_e32 v26, 0
	v_mov_b32_e32 v27, 0
	v_mov_b32_e32 v28, 1.0
	v_mov_b32_e32 v29, 1.0
	v_mov_b32_e32 v30, 1.0
	v_mov_b32_e32 v31, 1.0
	global_store_dwordx4 v[4:5], v[0:3], off offset:256 nt
	s_cbranch_vccnz .LBB0_359
	s_nop 0
	v_mov_b32_e32 v0, s0
	v_cndmask_b32_e64 v0, v204, v0, s[6:7]
	v_lshlrev_b32_e32 v32, 6, v0
	v_lshl_add_u64 v[0:1], v[192:193], 0, v[32:33]
	v_lshl_add_u64 v[2:3], v[194:195], 0, v[32:33]
	global_load_dwordx4 v[28:31], v[0:1], off
	global_load_dwordx4 v[24:27], v[2:3], off

.LBB0_365:
	v_lshlrev_b64 v[166:167], 13, v[202:203]
	v_lshl_add_u64 v[168:169], v[198:199], 0, v[166:167]
	s_waitcnt vmcnt(0)
	v_pk_mul_f32 v[166:167], v[96:97], v[26:27]
	v_pk_mul_f32 v[170:171], v[94:95], v[24:25]
	v_pk_mul_f32 v[172:173], v[96:97], v[30:31]
	v_pk_mul_f32 v[176:177], v[94:95], v[28:29]
	v_pk_fma_f32 v[166:167], v[100:101], v[30:31], v[166:167] neg_lo:[0,0,1] neg_hi:[0,0,1]
	v_pk_fma_f32 v[170:171], v[98:99], v[28:29], v[170:171] neg_lo:[0,0,1] neg_hi:[0,0,1]
	v_pk_fma_f32 v[172:173], v[100:101], v[26:27], v[172:173]
	v_pk_fma_f32 v[176:177], v[98:99], v[24:25], v[176:177]
	v_mov_b32_e32 v197, v196
	v_cndmask_b32_e64 v179, v101, v167, s[8:9]
	v_cndmask_b32_e64 v178, v100, v166, s[8:9]
	v_cndmask_b32_e64 v171, v99, v171, s[8:9]
	v_cndmask_b32_e64 v170, v98, v170, s[8:9]
	v_cndmask_b32_e64 v173, v97, v173, s[8:9]
	v_cndmask_b32_e64 v172, v96, v172, s[8:9]
	v_cndmask_b32_e64 v177, v95, v177, s[8:9]
	v_cndmask_b32_e64 v176, v94, v176, s[8:9]
	v_mov_b32_e32 v166, v196
	v_mov_b32_e32 v167, v196
	s_mov_b32 s0, 0x100000
	v_pk_mul_f32 v[178:179], v[166:167], v[178:179]
	v_pk_mul_f32 v[170:171], v[196:197], v[170:171]
	v_pk_mul_f32 v[180:181], v[166:167], v[172:173]
	v_pk_mul_f32 v[172:173], v[196:197], v[176:177]
	v_add_co_u32_e32 v176, vcc, s0, v168
	v_cvt_pk_bf16_f32 v170, v170, v171
	v_cvt_pk_bf16_f32 v171, v178, v179
	v_cvt_pk_bf16_f32 v172, v172, v173
	v_cvt_pk_bf16_f32 v173, v180, v181
	v_addc_co_u32_e32 v177, vcc, 0, v169, vcc
	global_store_dwordx4 v[176:177], v[170:173], off nt
	s_mov_b64 s[12:13], 0x100000
	v_lshl_add_u64 v[174:175], v[168:169], 0, s[12:13]
	v_pk_mul_f32 v[170:171], v[88:89], v[26:27]
	v_pk_mul_f32 v[172:173], v[86:87], v[24:25]
	v_pk_fma_f32 v[170:171], v[92:93], v[30:31], v[170:171] neg_lo:[0,0,1] neg_hi:[0,0,1]
	v_pk_fma_f32 v[172:173], v[90:91], v[28:29], v[172:173] neg_lo:[0,0,1] neg_hi:[0,0,1]
	v_pk_mul_f32 v[30:31], v[88:89], v[30:31]
	v_pk_mul_f32 v[28:29], v[86:87], v[28:29]
	v_pk_fma_f32 v[26:27], v[92:93], v[26:27], v[30:31]
	v_pk_fma_f32 v[24:25], v[90:91], v[24:25], v[28:29]
	v_cndmask_b32_e64 v29, v93, v171, s[10:11]
	v_cndmask_b32_e64 v28, v92, v170, s[10:11]
	v_cndmask_b32_e64 v31, v91, v173, s[10:11]
	v_cndmask_b32_e64 v30, v90, v172, s[10:11]
	v_cndmask_b32_e64 v27, v89, v27, s[10:11]
	v_cndmask_b32_e64 v26, v88, v26, s[10:11]
	v_cndmask_b32_e64 v25, v87, v25, s[10:11]
	v_cndmask_b32_e64 v24, v86, v24, s[10:11]
	v_pk_mul_f32 v[28:29], v[166:167], v[28:29]
	v_pk_mul_f32 v[30:31], v[196:197], v[30:31]
	v_pk_mul_f32 v[170:171], v[166:167], v[26:27]
	v_pk_mul_f32 v[26:27], v[196:197], v[24:25]
	v_cvt_pk_bf16_f32 v24, v30, v31
	v_cvt_pk_bf16_f32 v25, v28, v29
	v_cvt_pk_bf16_f32 v26, v26, v27
	v_cvt_pk_bf16_f32 v27, v170, v171
	global_store_dwordx4 v[174:175], v[24:27], off offset:256 nt
	v_pk_mul_f32 v[30:31], v[80:81], v[18:19]
	v_pk_mul_f32 v[170:171], v[78:79], v[16:17]
	v_pk_mul_f32 v[24:25], v[80:81], v[10:11]
	v_pk_mul_f32 v[26:27], v[78:79], v[8:9]
	v_pk_fma_f32 v[24:25], v[84:85], v[18:19], v[24:25] neg_lo:[0,0,1] neg_hi:[0,0,1]
	v_pk_fma_f32 v[26:27], v[82:83], v[16:17], v[26:27] neg_lo:[0,0,1] neg_hi:[0,0,1]
	v_pk_fma_f32 v[30:31], v[84:85], v[10:11], v[30:31]
	v_pk_fma_f32 v[170:171], v[82:83], v[8:9], v[170:171]
	v_cndmask_b32_e64 v27, v83, v27, s[8:9]
	v_cndmask_b32_e64 v26, v82, v26, s[8:9]
	v_cndmask_b32_e64 v25, v85, v25, s[8:9]
	v_cndmask_b32_e64 v24, v84, v24, s[8:9]
	v_cndmask_b32_e64 v171, v79, v171, s[8:9]
	v_cndmask_b32_e64 v170, v78, v170, s[8:9]
	v_cndmask_b32_e64 v31, v81, v31, s[8:9]
	v_cndmask_b32_e64 v30, v80, v30, s[8:9]
	v_pk_mul_f32 v[172:173], v[166:167], v[24:25]
	v_pk_mul_f32 v[24:25], v[196:197], v[26:27]
	v_pk_mul_f32 v[30:31], v[166:167], v[30:31]
	v_pk_mul_f32 v[26:27], v[196:197], v[170:171]
	s_mov_b32 s0, 0x120000
	v_cvt_pk_bf16_f32 v26, v26, v27
	v_cvt_pk_bf16_f32 v27, v30, v31
	v_add_co_u32_e32 v30, vcc, s0, v168
	v_cvt_pk_bf16_f32 v24, v24, v25
	v_cvt_pk_bf16_f32 v25, v172, v173
	v_addc_co_u32_e32 v31, vcc, 0, v169, vcc
	global_store_dwordx4 v[30:31], v[24:27], off nt
	s_mov_b64 s[12:13], 0x120000
	v_lshl_add_u64 v[28:29], v[168:169], 0, s[12:13]
	v_pk_mul_f32 v[24:25], v[72:73], v[10:11]
	v_pk_mul_f32 v[26:27], v[70:71], v[8:9]
	v_pk_fma_f32 v[24:25], v[76:77], v[18:19], v[24:25] neg_lo:[0,0,1] neg_hi:[0,0,1]
	v_pk_fma_f32 v[26:27], v[74:75], v[16:17], v[26:27] neg_lo:[0,0,1] neg_hi:[0,0,1]
	v_pk_mul_f32 v[18:19], v[72:73], v[18:19]
	v_pk_mul_f32 v[16:17], v[70:71], v[16:17]
	v_pk_fma_f32 v[10:11], v[76:77], v[10:11], v[18:19]
	v_pk_fma_f32 v[8:9], v[74:75], v[8:9], v[16:17]
	v_cndmask_b32_e64 v17, v75, v27, s[10:11]
	v_cndmask_b32_e64 v16, v74, v26, s[10:11]
	v_cndmask_b32_e64 v19, v77, v25, s[10:11]
	v_cndmask_b32_e64 v18, v76, v24, s[10:11]
	v_cndmask_b32_e64 v9, v71, v9, s[10:11]
	v_cndmask_b32_e64 v8, v70, v8, s[10:11]
	v_cndmask_b32_e64 v11, v73, v11, s[10:11]
	v_cndmask_b32_e64 v10, v72, v10, s[10:11]
	v_pk_mul_f32 v[18:19], v[166:167], v[18:19]
	v_pk_mul_f32 v[16:17], v[196:197], v[16:17]
	v_pk_mul_f32 v[24:25], v[166:167], v[10:11]
	v_pk_mul_f32 v[10:11], v[196:197], v[8:9]
	v_cvt_pk_bf16_f32 v8, v16, v17
	v_cvt_pk_bf16_f32 v9, v18, v19
	v_cvt_pk_bf16_f32 v10, v10, v11
	v_cvt_pk_bf16_f32 v11, v24, v25
	global_store_dwordx4 v[28:29], v[8:11], off offset:256 nt
	v_pk_mul_f32 v[18:19], v[64:65], v[22:23]
	v_pk_mul_f32 v[24:25], v[62:63], v[20:21]
	v_pk_mul_f32 v[8:9], v[64:65], v[14:15]
	v_pk_mul_f32 v[10:11], v[62:63], v[12:13]
	v_pk_fma_f32 v[8:9], v[68:69], v[22:23], v[8:9] neg_lo:[0,0,1] neg_hi:[0,0,1]
	v_pk_fma_f32 v[10:11], v[66:67], v[20:21], v[10:11] neg_lo:[0,0,1] neg_hi:[0,0,1]
	v_pk_fma_f32 v[18:19], v[68:69], v[14:15], v[18:19]
	v_pk_fma_f32 v[24:25], v[66:67], v[12:13], v[24:25]
	v_cndmask_b32_e64 v11, v67, v11, s[8:9]
	v_cndmask_b32_e64 v10, v66, v10, s[8:9]
	v_cndmask_b32_e64 v9, v69, v9, s[8:9]
	v_cndmask_b32_e64 v8, v68, v8, s[8:9]
	v_cndmask_b32_e64 v25, v63, v25, s[8:9]
	v_cndmask_b32_e64 v24, v62, v24, s[8:9]
	v_cndmask_b32_e64 v19, v65, v19, s[8:9]
	v_cndmask_b32_e64 v18, v64, v18, s[8:9]
	v_pk_mul_f32 v[26:27], v[166:167], v[8:9]
	v_pk_mul_f32 v[8:9], v[196:197], v[10:11]
	v_pk_mul_f32 v[18:19], v[166:167], v[18:19]
	v_pk_mul_f32 v[10:11], v[196:197], v[24:25]
	s_mov_b32 s0, 0x140000
	v_cvt_pk_bf16_f32 v10, v10, v11
	v_cvt_pk_bf16_f32 v11, v18, v19
	v_add_co_u32_e32 v18, vcc, s0, v168
	v_cvt_pk_bf16_f32 v8, v8, v9
	v_cvt_pk_bf16_f32 v9, v26, v27
	v_addc_co_u32_e32 v19, vcc, 0, v169, vcc
	global_store_dwordx4 v[18:19], v[8:11], off nt
	v_pk_mul_f32 v[18:19], v[56:57], v[22:23]
	s_mov_b64 s[12:13], 0x140000
	v_pk_mul_f32 v[10:11], v[54:55], v[12:13]
	v_pk_mul_f32 v[8:9], v[56:57], v[14:15]
	v_pk_fma_f32 v[10:11], v[58:59], v[20:21], v[10:11] neg_lo:[0,0,1] neg_hi:[0,0,1]
	v_pk_mul_f32 v[20:21], v[54:55], v[20:21]
	v_pk_fma_f32 v[8:9], v[60:61], v[22:23], v[8:9] neg_lo:[0,0,1] neg_hi:[0,0,1]
	v_pk_fma_f32 v[14:15], v[60:61], v[14:15], v[18:19]
	v_pk_fma_f32 v[12:13], v[58:59], v[12:13], v[20:21]
	v_cndmask_b32_e64 v11, v59, v11, s[10:11]
	v_cndmask_b32_e64 v10, v58, v10, s[10:11]
	v_cndmask_b32_e64 v9, v61, v9, s[10:11]
	v_cndmask_b32_e64 v8, v60, v8, s[10:11]
	v_cndmask_b32_e64 v13, v55, v13, s[10:11]
	v_cndmask_b32_e64 v12, v54, v12, s[10:11]
	v_cndmask_b32_e64 v15, v57, v15, s[10:11]
	v_cndmask_b32_e64 v14, v56, v14, s[10:11]
	v_pk_mul_f32 v[18:19], v[166:167], v[8:9]
	v_pk_mul_f32 v[8:9], v[196:197], v[10:11]
	v_pk_mul_f32 v[14:15], v[166:167], v[14:15]
	v_pk_mul_f32 v[10:11], v[196:197], v[12:13]
	v_lshl_add_u64 v[16:17], v[168:169], 0, s[12:13]
	v_cvt_pk_bf16_f32 v8, v8, v9
	v_cvt_pk_bf16_f32 v9, v18, v19
	v_cvt_pk_bf16_f32 v10, v10, v11
	v_cvt_pk_bf16_f32 v11, v14, v15
	global_store_dwordx4 v[16:17], v[8:11], off offset:256 nt
	v_pk_mul_f32 v[14:15], v[48:49], v[2:3]
	v_pk_mul_f32 v[16:17], v[46:47], v[0:1]
	v_pk_mul_f32 v[8:9], v[48:49], v[6:7]
	v_pk_mul_f32 v[10:11], v[46:47], v[4:5]
	v_pk_fma_f32 v[8:9], v[52:53], v[2:3], v[8:9] neg_lo:[0,0,1] neg_hi:[0,0,1]
	v_pk_fma_f32 v[10:11], v[50:51], v[0:1], v[10:11] neg_lo:[0,0,1] neg_hi:[0,0,1]
	v_pk_fma_f32 v[14:15], v[52:53], v[6:7], v[14:15]
	v_pk_fma_f32 v[16:17], v[50:51], v[4:5], v[16:17]
	v_cndmask_b32_e64 v11, v51, v11, s[8:9]
	v_cndmask_b32_e64 v10, v50, v10, s[8:9]
	v_cndmask_b32_e64 v9, v53, v9, s[8:9]
	v_cndmask_b32_e64 v8, v52, v8, s[8:9]
	v_cndmask_b32_e64 v17, v47, v17, s[8:9]
	v_cndmask_b32_e64 v16, v46, v16, s[8:9]
	v_cndmask_b32_e64 v15, v49, v15, s[8:9]
	v_cndmask_b32_e64 v14, v48, v14, s[8:9]
	v_pk_mul_f32 v[18:19], v[166:167], v[8:9]
	v_pk_mul_f32 v[8:9], v[196:197], v[10:11]
	v_pk_mul_f32 v[14:15], v[166:167], v[14:15]
	v_pk_mul_f32 v[10:11], v[196:197], v[16:17]
	s_mov_b32 s0, 0x160000
	v_cvt_pk_bf16_f32 v10, v10, v11
	v_cvt_pk_bf16_f32 v11, v14, v15
	v_add_co_u32_e32 v14, vcc, s0, v168
	v_cvt_pk_bf16_f32 v8, v8, v9
	v_cvt_pk_bf16_f32 v9, v18, v19
	v_addc_co_u32_e32 v15, vcc, 0, v169, vcc
	global_store_dwordx4 v[14:15], v[8:11], off nt
	s_mov_b64 s[12:13], 0x160000
	v_lshl_add_u64 v[12:13], v[168:169], 0, s[12:13]
	v_pk_mul_f32 v[8:9], v[40:41], v[6:7]
	v_pk_mul_f32 v[10:11], v[38:39], v[4:5]
	v_pk_fma_f32 v[8:9], v[44:45], v[2:3], v[8:9] neg_lo:[0,0,1] neg_hi:[0,0,1]
	v_pk_fma_f32 v[10:11], v[42:43], v[0:1], v[10:11] neg_lo:[0,0,1] neg_hi:[0,0,1]
	v_pk_mul_f32 v[2:3], v[40:41], v[2:3]
	v_pk_mul_f32 v[0:1], v[38:39], v[0:1]
	v_pk_fma_f32 v[2:3], v[44:45], v[6:7], v[2:3]
	v_pk_fma_f32 v[0:1], v[42:43], v[4:5], v[0:1]
	v_cndmask_b32_e64 v5, v43, v11, s[10:11]
	v_cndmask_b32_e64 v4, v42, v10, s[10:11]
	v_cndmask_b32_e64 v7, v45, v9, s[10:11]
	v_cndmask_b32_e64 v6, v44, v8, s[10:11]
	v_cndmask_b32_e64 v1, v39, v1, s[10:11]
	v_cndmask_b32_e64 v0, v38, v0, s[10:11]
	v_cndmask_b32_e64 v3, v41, v3, s[10:11]
	v_cndmask_b32_e64 v2, v40, v2, s[10:11]
	v_pk_mul_f32 v[6:7], v[166:167], v[6:7]
	v_pk_mul_f32 v[4:5], v[196:197], v[4:5]
	v_pk_mul_f32 v[8:9], v[166:167], v[2:3]
	v_pk_mul_f32 v[2:3], v[196:197], v[0:1]
	v_cvt_pk_bf16_f32 v0, v4, v5
	v_cvt_pk_bf16_f32 v1, v6, v7
	v_cvt_pk_bf16_f32 v2, v2, v3
	v_cvt_pk_bf16_f32 v3, v8, v9
	global_store_dwordx4 v[12:13], v[0:3], off offset:256 nt

.LBB0_520:
	s_cmp_lt_i32 s72, 3
	s_cbranch_scc1 .Lpxa_gen_b
	s_add_i32 s0, s72, -9
	s_cmp_lt_u32 s0, 2
	s_cbranch_scc1 .Lpxa_gen_b
	s_lshl_b32 s0, s73, 8
	s_add_i32 s0, s0, s63
	v_or_b32_e32 v202, s0, v204
	s_lshl_b32 s10, s72, 8
	s_mov_b32 s11, 0
	v_lshl_add_u64 v[198:199], s[10:11], 1, v[188:189]
	v_mov_b32_e32 v203, 0
	v_lshlrev_b64 v[18:19], 13, v[202:203]
	v_lshl_add_u64 v[22:23], v[198:199], 0, v[18:19]
	v_cvt_pk_bf16_f32 v0, v162, v163
	v_cvt_pk_bf16_f32 v1, v164, v165
	v_cvt_pk_bf16_f32 v2, v158, v159
	v_cvt_pk_bf16_f32 v3, v160, v161
	global_store_dwordx4 v[22:23], v[0:3], off nt
	v_cvt_pk_bf16_f32 v4, v154, v155
	v_cvt_pk_bf16_f32 v5, v156, v157
	v_cvt_pk_bf16_f32 v6, v150, v151
	v_cvt_pk_bf16_f32 v7, v152, v153
	global_store_dwordx4 v[22:23], v[4:7], off offset:256 nt
	s_mov_b32 s8, 0x20000
	s_mov_b32 s9, 0
	v_lshl_add_u64 v[26:27], v[22:23], 0, s[8:9]
	v_cvt_pk_bf16_f32 v8, v146, v147
	v_cvt_pk_bf16_f32 v9, v148, v149
	v_cvt_pk_bf16_f32 v10, v142, v143
	v_cvt_pk_bf16_f32 v11, v144, v145
	global_store_dwordx4 v[26:27], v[8:11], off nt
	v_cvt_pk_bf16_f32 v12, v138, v139
	v_cvt_pk_bf16_f32 v13, v140, v141
	v_cvt_pk_bf16_f32 v14, v134, v135
	v_cvt_pk_bf16_f32 v15, v136, v137
	global_store_dwordx4 v[26:27], v[12:15], off offset:256 nt
	s_mov_b32 s8, 0x40000
	s_mov_b32 s9, 0
	v_lshl_add_u64 v[28:29], v[22:23], 0, s[8:9]
	v_cvt_pk_bf16_f32 v0, v130, v131
	v_cvt_pk_bf16_f32 v1, v132, v133
	v_cvt_pk_bf16_f32 v2, v126, v127
	v_cvt_pk_bf16_f32 v3, v128, v129
	global_store_dwordx4 v[28:29], v[0:3], off nt
	v_cvt_pk_bf16_f32 v4, v122, v123
	v_cvt_pk_bf16_f32 v5, v124, v125
	v_cvt_pk_bf16_f32 v6, v118, v119
	v_cvt_pk_bf16_f32 v7, v120, v121
	global_store_dwordx4 v[28:29], v[4:7], off offset:256 nt
	s_mov_b32 s8, 0x60000
	s_mov_b32 s9, 0
	v_lshl_add_u64 v[24:25], v[22:23], 0, s[8:9]
	v_cvt_pk_bf16_f32 v8, v114, v115
	v_cvt_pk_bf16_f32 v9, v116, v117
	v_cvt_pk_bf16_f32 v10, v110, v111
	v_cvt_pk_bf16_f32 v11, v112, v113
	global_store_dwordx4 v[24:25], v[8:11], off nt
	v_cvt_pk_bf16_f32 v12, v106, v107
	v_cvt_pk_bf16_f32 v13, v108, v109
	v_cvt_pk_bf16_f32 v14, v102, v103
	v_cvt_pk_bf16_f32 v15, v104, v105
	global_store_dwordx4 v[24:25], v[12:15], off offset:256 nt
	s_mov_b32 s8, 0x100000
	s_mov_b32 s9, 0
	v_lshl_add_u64 v[26:27], v[22:23], 0, s[8:9]
	v_cvt_pk_bf16_f32 v0, v98, v99
	v_cvt_pk_bf16_f32 v1, v100, v101
	v_cvt_pk_bf16_f32 v2, v94, v95
	v_cvt_pk_bf16_f32 v3, v96, v97
	global_store_dwordx4 v[26:27], v[0:3], off nt
	v_cvt_pk_bf16_f32 v4, v90, v91
	v_cvt_pk_bf16_f32 v5, v92, v93
	v_cvt_pk_bf16_f32 v6, v86, v87
	v_cvt_pk_bf16_f32 v7, v88, v89
	global_store_dwordx4 v[26:27], v[4:7], off offset:256 nt
	s_mov_b32 s8, 0x120000
	s_mov_b32 s9, 0
	v_lshl_add_u64 v[28:29], v[22:23], 0, s[8:9]
	v_cvt_pk_bf16_f32 v8, v82, v83
	v_cvt_pk_bf16_f32 v9, v84, v85
	v_cvt_pk_bf16_f32 v10, v78, v79
	v_cvt_pk_bf16_f32 v11, v80, v81
	global_store_dwordx4 v[28:29], v[8:11], off nt
	v_cvt_pk_bf16_f32 v12, v74, v75
	v_cvt_pk_bf16_f32 v13, v76, v77
	v_cvt_pk_bf16_f32 v14, v70, v71
	v_cvt_pk_bf16_f32 v15, v72, v73
	global_store_dwordx4 v[28:29], v[12:15], off offset:256 nt
	s_mov_b32 s8, 0x140000
	s_mov_b32 s9, 0
	v_lshl_add_u64 v[24:25], v[22:23], 0, s[8:9]
	v_cvt_pk_bf16_f32 v0, v66, v67
	v_cvt_pk_bf16_f32 v1, v68, v69
	v_cvt_pk_bf16_f32 v2, v62, v63
	v_cvt_pk_bf16_f32 v3, v64, v65
	global_store_dwordx4 v[24:25], v[0:3], off nt
	v_cvt_pk_bf16_f32 v4, v58, v59
	v_cvt_pk_bf16_f32 v5, v60, v61
	v_cvt_pk_bf16_f32 v6, v54, v55
	v_cvt_pk_bf16_f32 v7, v56, v57
	global_store_dwordx4 v[24:25], v[4:7], off offset:256 nt
	s_mov_b32 s8, 0x160000
	s_mov_b32 s9, 0
	v_lshl_add_u64 v[26:27], v[22:23], 0, s[8:9]
	v_cvt_pk_bf16_f32 v8, v50, v51
	v_cvt_pk_bf16_f32 v9, v52, v53
	v_cvt_pk_bf16_f32 v10, v46, v47
	v_cvt_pk_bf16_f32 v11, v48, v49
	global_store_dwordx4 v[26:27], v[8:11], off nt
	v_cvt_pk_bf16_f32 v12, v42, v43
	v_cvt_pk_bf16_f32 v13, v44, v45
	v_cvt_pk_bf16_f32 v14, v38, v39
	v_cvt_pk_bf16_f32 v15, v40, v41
	global_store_dwordx4 v[26:27], v[12:15], off offset:256 nt
	s_branch .LBB0_538

.LBB0_529:
	s_cmp_eq_u32 s72, 10
	s_cselect_b64 vcc, -1, 0
	v_cndmask_b32_e32 v17, 1.0, v224, vcc
	v_mov_b32_e32 v18, 0x3e38aa3b
	v_cndmask_b32_e64 v196, v17, v18, s[10:11]
	s_lshl_b32 s10, s72, 8
	v_or_b32_e32 v202, s0, v204
	s_ashr_i32 s11, s10, 31
	v_ashrrev_i32_e32 v203, 31, v202
	v_lshl_add_u64 v[198:199], s[10:11], 1, v[188:189]
	v_lshlrev_b64 v[18:19], 13, v[202:203]
	v_lshl_add_u64 v[22:23], v[198:199], 0, v[18:19]
	v_pk_mul_f32 v[18:19], v[160:161], v[2:3]
	v_pk_mul_f32 v[20:21], v[158:159], v[0:1]
	v_pk_mul_f32 v[24:25], v[160:161], v[180:181]
	v_pk_mul_f32 v[26:27], v[158:159], v[178:179]
	v_pk_fma_f32 v[18:19], v[164:165], v[180:181], v[18:19] neg_lo:[0,0,1] neg_hi:[0,0,1]
	v_pk_fma_f32 v[20:21], v[162:163], v[178:179], v[20:21] neg_lo:[0,0,1] neg_hi:[0,0,1]
	v_pk_fma_f32 v[24:25], v[164:165], v[2:3], v[24:25]
	v_pk_fma_f32 v[26:27], v[162:163], v[0:1], v[26:27]
	v_cndmask_b32_e64 v19, v165, v19, s[8:9]
	v_cndmask_b32_e64 v18, v164, v18, s[8:9]
	v_cndmask_b32_e64 v21, v163, v21, s[8:9]
	v_cndmask_b32_e64 v20, v162, v20, s[8:9]
	v_cndmask_b32_e64 v25, v161, v25, s[8:9]
	v_cndmask_b32_e64 v24, v160, v24, s[8:9]
	v_cndmask_b32_e64 v27, v159, v27, s[8:9]
	v_cndmask_b32_e64 v26, v158, v26, s[8:9]
	v_pk_mul_f32 v[28:29], v[196:197], v[18:19] op_sel_hi:[0,1]
	v_pk_mul_f32 v[18:19], v[196:197], v[20:21] op_sel_hi:[0,1]
	v_pk_mul_f32 v[24:25], v[196:197], v[24:25] op_sel_hi:[0,1]
	v_pk_mul_f32 v[20:21], v[196:197], v[26:27] op_sel_hi:[0,1]
	v_cvt_pk_bf16_f32 v18, v18, v19
	v_cvt_pk_bf16_f32 v19, v28, v29
	v_cvt_pk_bf16_f32 v20, v20, v21
	v_cvt_pk_bf16_f32 v21, v24, v25
	global_store_dwordx4 v[22:23], v[18:21], off nt
	v_pk_mul_f32 v[24:25], v[152:153], v[180:181]
	v_pk_mul_f32 v[26:27], v[150:151], v[178:179]
	v_pk_mul_f32 v[18:19], v[152:153], v[2:3]
	v_pk_mul_f32 v[20:21], v[150:151], v[0:1]
	v_pk_fma_f32 v[18:19], v[156:157], v[180:181], v[18:19] neg_lo:[0,0,1] neg_hi:[0,0,1]
	v_pk_fma_f32 v[20:21], v[154:155], v[178:179], v[20:21] neg_lo:[0,0,1] neg_hi:[0,0,1]
	v_pk_fma_f32 v[2:3], v[156:157], v[2:3], v[24:25]
	v_pk_fma_f32 v[0:1], v[154:155], v[0:1], v[26:27]
	s_and_b64 s[10:11], s[40:41], s[34:35]
	v_cndmask_b32_e64 v21, v155, v21, s[10:11]
	v_cndmask_b32_e64 v20, v154, v20, s[10:11]
	v_cndmask_b32_e64 v19, v157, v19, s[10:11]
	v_cndmask_b32_e64 v18, v156, v18, s[10:11]
	v_cndmask_b32_e64 v1, v151, v1, s[10:11]
	v_cndmask_b32_e64 v0, v150, v0, s[10:11]
	v_cndmask_b32_e64 v3, v153, v3, s[10:11]
	v_cndmask_b32_e64 v2, v152, v2, s[10:11]
	v_pk_mul_f32 v[18:19], v[196:197], v[18:19] op_sel_hi:[0,1]
	v_pk_mul_f32 v[20:21], v[196:197], v[20:21] op_sel_hi:[0,1]
	v_pk_mul_f32 v[24:25], v[196:197], v[2:3] op_sel_hi:[0,1]
	v_pk_mul_f32 v[2:3], v[196:197], v[0:1] op_sel_hi:[0,1]
	v_cvt_pk_bf16_f32 v0, v20, v21
	v_cvt_pk_bf16_f32 v1, v18, v19
	v_cvt_pk_bf16_f32 v2, v2, v3
	v_cvt_pk_bf16_f32 v3, v24, v25
	global_store_dwordx4 v[22:23], v[0:3], off offset:256 nt
	v_pk_mul_f32 v[20:21], v[144:145], v[176:177]
	v_pk_mul_f32 v[22:23], v[142:143], v[174:175]
	v_or_b32_e32 v0, 16, v202
	v_ashrrev_i32_e32 v1, 31, v0
	v_lshlrev_b64 v[0:1], 13, v[0:1]
	v_lshl_add_u64 v[18:19], v[198:199], 0, v[0:1]
	v_pk_mul_f32 v[0:1], v[144:145], v[6:7]
	v_pk_mul_f32 v[2:3], v[142:143], v[4:5]
	v_pk_fma_f32 v[0:1], v[148:149], v[176:177], v[0:1] neg_lo:[0,0,1] neg_hi:[0,0,1]
	v_pk_fma_f32 v[2:3], v[146:147], v[174:175], v[2:3] neg_lo:[0,0,1] neg_hi:[0,0,1]
	v_pk_fma_f32 v[20:21], v[148:149], v[6:7], v[20:21]
	v_pk_fma_f32 v[22:23], v[146:147], v[4:5], v[22:23]
	v_cndmask_b32_e64 v3, v147, v3, s[8:9]
	v_cndmask_b32_e64 v2, v146, v2, s[8:9]
	v_cndmask_b32_e64 v1, v149, v1, s[8:9]
	v_cndmask_b32_e64 v0, v148, v0, s[8:9]
	v_cndmask_b32_e64 v23, v143, v23, s[8:9]
	v_cndmask_b32_e64 v22, v142, v22, s[8:9]
	v_cndmask_b32_e64 v21, v145, v21, s[8:9]
	v_cndmask_b32_e64 v20, v144, v20, s[8:9]
	v_pk_mul_f32 v[24:25], v[196:197], v[0:1] op_sel_hi:[0,1]
	v_pk_mul_f32 v[0:1], v[196:197], v[2:3] op_sel_hi:[0,1]
	v_pk_mul_f32 v[20:21], v[196:197], v[20:21] op_sel_hi:[0,1]
	v_pk_mul_f32 v[2:3], v[196:197], v[22:23] op_sel_hi:[0,1]
	v_cvt_pk_bf16_f32 v0, v0, v1
	v_cvt_pk_bf16_f32 v1, v24, v25
	v_cvt_pk_bf16_f32 v2, v2, v3
	v_cvt_pk_bf16_f32 v3, v20, v21
	global_store_dwordx4 v[18:19], v[0:3], off nt
	v_pk_mul_f32 v[20:21], v[136:137], v[176:177]
	v_pk_mul_f32 v[22:23], v[134:135], v[174:175]
	v_pk_mul_f32 v[0:1], v[136:137], v[6:7]
	v_pk_mul_f32 v[2:3], v[134:135], v[4:5]
	v_pk_fma_f32 v[0:1], v[140:141], v[176:177], v[0:1] neg_lo:[0,0,1] neg_hi:[0,0,1]
	v_pk_fma_f32 v[2:3], v[138:139], v[174:175], v[2:3] neg_lo:[0,0,1] neg_hi:[0,0,1]
	v_pk_fma_f32 v[6:7], v[140:141], v[6:7], v[20:21]
	v_pk_fma_f32 v[4:5], v[138:139], v[4:5], v[22:23]
	v_cndmask_b32_e64 v3, v139, v3, s[10:11]
	v_cndmask_b32_e64 v2, v138, v2, s[10:11]
	v_cndmask_b32_e64 v1, v141, v1, s[10:11]
	v_cndmask_b32_e64 v0, v140, v0, s[10:11]
	v_cndmask_b32_e64 v5, v135, v5, s[10:11]
	v_cndmask_b32_e64 v4, v134, v4, s[10:11]
	v_cndmask_b32_e64 v7, v137, v7, s[10:11]
	v_cndmask_b32_e64 v6, v136, v6, s[10:11]
	v_pk_mul_f32 v[20:21], v[196:197], v[0:1] op_sel_hi:[0,1]
	v_pk_mul_f32 v[0:1], v[196:197], v[2:3] op_sel_hi:[0,1]
	v_pk_mul_f32 v[6:7], v[196:197], v[6:7] op_sel_hi:[0,1]
	v_pk_mul_f32 v[2:3], v[196:197], v[4:5] op_sel_hi:[0,1]
	v_cvt_pk_bf16_f32 v0, v0, v1
	v_cvt_pk_bf16_f32 v1, v20, v21
	v_cvt_pk_bf16_f32 v2, v2, v3
	v_cvt_pk_bf16_f32 v3, v6, v7
	global_store_dwordx4 v[18:19], v[0:3], off offset:256 nt
	s_waitcnt vmcnt(4)
	v_pk_mul_f32 v[6:7], v[128:129], v[172:173]
	v_pk_mul_f32 v[18:19], v[126:127], v[170:171]
	v_or_b32_e32 v0, 32, v202
	v_ashrrev_i32_e32 v1, 31, v0
	v_lshlrev_b64 v[0:1], 13, v[0:1]
	v_lshl_add_u64 v[4:5], v[198:199], 0, v[0:1]
	v_pk_mul_f32 v[0:1], v[128:129], v[10:11]
	v_pk_mul_f32 v[2:3], v[126:127], v[8:9]
	v_pk_fma_f32 v[0:1], v[132:133], v[172:173], v[0:1] neg_lo:[0,0,1] neg_hi:[0,0,1]
	v_pk_fma_f32 v[2:3], v[130:131], v[170:171], v[2:3] neg_lo:[0,0,1] neg_hi:[0,0,1]
	v_pk_fma_f32 v[6:7], v[132:133], v[10:11], v[6:7]
	v_pk_fma_f32 v[18:19], v[130:131], v[8:9], v[18:19]
	v_cndmask_b32_e64 v3, v131, v3, s[8:9]
	v_cndmask_b32_e64 v2, v130, v2, s[8:9]
	v_cndmask_b32_e64 v1, v133, v1, s[8:9]
	v_cndmask_b32_e64 v0, v132, v0, s[8:9]
	v_cndmask_b32_e64 v19, v127, v19, s[8:9]
	v_cndmask_b32_e64 v18, v126, v18, s[8:9]
	v_cndmask_b32_e64 v7, v129, v7, s[8:9]
	v_cndmask_b32_e64 v6, v128, v6, s[8:9]
	v_pk_mul_f32 v[20:21], v[196:197], v[0:1] op_sel_hi:[0,1]
	v_pk_mul_f32 v[0:1], v[196:197], v[2:3] op_sel_hi:[0,1]
	v_pk_mul_f32 v[6:7], v[196:197], v[6:7] op_sel_hi:[0,1]
	v_pk_mul_f32 v[2:3], v[196:197], v[18:19] op_sel_hi:[0,1]
	v_cvt_pk_bf16_f32 v0, v0, v1
	v_cvt_pk_bf16_f32 v1, v20, v21
	v_cvt_pk_bf16_f32 v2, v2, v3
	v_cvt_pk_bf16_f32 v3, v6, v7
	global_store_dwordx4 v[4:5], v[0:3], off nt
	v_pk_mul_f32 v[6:7], v[120:121], v[172:173]
	v_pk_mul_f32 v[18:19], v[118:119], v[170:171]
	v_pk_mul_f32 v[0:1], v[120:121], v[10:11]
	v_pk_mul_f32 v[2:3], v[118:119], v[8:9]
	v_pk_fma_f32 v[0:1], v[124:125], v[172:173], v[0:1] neg_lo:[0,0,1] neg_hi:[0,0,1]
	v_pk_fma_f32 v[2:3], v[122:123], v[170:171], v[2:3] neg_lo:[0,0,1] neg_hi:[0,0,1]
	v_pk_fma_f32 v[6:7], v[124:125], v[10:11], v[6:7]
	v_pk_fma_f32 v[8:9], v[122:123], v[8:9], v[18:19]
	v_cndmask_b32_e64 v3, v123, v3, s[10:11]
	v_cndmask_b32_e64 v2, v122, v2, s[10:11]
	v_cndmask_b32_e64 v1, v125, v1, s[10:11]
	v_cndmask_b32_e64 v0, v124, v0, s[10:11]
	v_cndmask_b32_e64 v9, v119, v9, s[10:11]
	v_cndmask_b32_e64 v8, v118, v8, s[10:11]
	v_cndmask_b32_e64 v7, v121, v7, s[10:11]
	v_cndmask_b32_e64 v6, v120, v6, s[10:11]
	v_pk_mul_f32 v[10:11], v[196:197], v[0:1] op_sel_hi:[0,1]
	v_pk_mul_f32 v[0:1], v[196:197], v[2:3] op_sel_hi:[0,1]
	v_pk_mul_f32 v[6:7], v[196:197], v[6:7] op_sel_hi:[0,1]
	v_pk_mul_f32 v[2:3], v[196:197], v[8:9] op_sel_hi:[0,1]
	v_cvt_pk_bf16_f32 v0, v0, v1
	v_cvt_pk_bf16_f32 v1, v10, v11
	v_cvt_pk_bf16_f32 v2, v2, v3
	v_cvt_pk_bf16_f32 v3, v6, v7
	global_store_dwordx4 v[4:5], v[0:3], off offset:256 nt
	v_pk_mul_f32 v[6:7], v[112:113], v[168:169]
	v_pk_mul_f32 v[8:9], v[110:111], v[166:167]
	v_or_b32_e32 v0, 48, v202
	v_ashrrev_i32_e32 v1, 31, v0
	v_lshlrev_b64 v[0:1], 13, v[0:1]
	v_lshl_add_u64 v[4:5], v[198:199], 0, v[0:1]
	v_pk_mul_f32 v[0:1], v[112:113], v[14:15]
	v_pk_mul_f32 v[2:3], v[110:111], v[12:13]
	v_pk_fma_f32 v[0:1], v[116:117], v[168:169], v[0:1] neg_lo:[0,0,1] neg_hi:[0,0,1]
	v_pk_fma_f32 v[2:3], v[114:115], v[166:167], v[2:3] neg_lo:[0,0,1] neg_hi:[0,0,1]
	v_pk_fma_f32 v[6:7], v[116:117], v[14:15], v[6:7]
	v_pk_fma_f32 v[8:9], v[114:115], v[12:13], v[8:9]
	v_cndmask_b32_e64 v3, v115, v3, s[8:9]
	v_cndmask_b32_e64 v2, v114, v2, s[8:9]
	v_cndmask_b32_e64 v1, v117, v1, s[8:9]
	v_cndmask_b32_e64 v0, v116, v0, s[8:9]
	v_cndmask_b32_e64 v9, v111, v9, s[8:9]
	v_cndmask_b32_e64 v8, v110, v8, s[8:9]
	v_cndmask_b32_e64 v7, v113, v7, s[8:9]
	v_cndmask_b32_e64 v6, v112, v6, s[8:9]
	v_pk_mul_f32 v[10:11], v[196:197], v[0:1] op_sel_hi:[0,1]
	v_pk_mul_f32 v[0:1], v[196:197], v[2:3] op_sel_hi:[0,1]
	v_pk_mul_f32 v[6:7], v[196:197], v[6:7] op_sel_hi:[0,1]
	v_pk_mul_f32 v[2:3], v[196:197], v[8:9] op_sel_hi:[0,1]
	v_cvt_pk_bf16_f32 v0, v0, v1
	v_cvt_pk_bf16_f32 v1, v10, v11
	v_cvt_pk_bf16_f32 v2, v2, v3
	v_cvt_pk_bf16_f32 v3, v6, v7
	global_store_dwordx4 v[4:5], v[0:3], off nt
	v_pk_mul_f32 v[6:7], v[104:105], v[168:169]
	v_pk_mul_f32 v[8:9], v[102:103], v[166:167]
	v_pk_mul_f32 v[0:1], v[104:105], v[14:15]
	v_pk_mul_f32 v[2:3], v[102:103], v[12:13]
	v_pk_fma_f32 v[0:1], v[108:109], v[168:169], v[0:1] neg_lo:[0,0,1] neg_hi:[0,0,1]
	v_pk_fma_f32 v[2:3], v[106:107], v[166:167], v[2:3] neg_lo:[0,0,1] neg_hi:[0,0,1]
	v_pk_fma_f32 v[6:7], v[108:109], v[14:15], v[6:7]
	v_pk_fma_f32 v[8:9], v[106:107], v[12:13], v[8:9]
	v_cndmask_b32_e64 v3, v107, v3, s[10:11]
	v_cndmask_b32_e64 v2, v106, v2, s[10:11]
	v_cndmask_b32_e64 v1, v109, v1, s[10:11]
	v_cndmask_b32_e64 v0, v108, v0, s[10:11]
	v_cndmask_b32_e64 v9, v103, v9, s[10:11]
	v_cndmask_b32_e64 v8, v102, v8, s[10:11]
	v_cndmask_b32_e64 v7, v105, v7, s[10:11]
	v_cndmask_b32_e64 v6, v104, v6, s[10:11]
	v_pk_mul_f32 v[10:11], v[196:197], v[0:1] op_sel_hi:[0,1]
	v_pk_mul_f32 v[0:1], v[196:197], v[2:3] op_sel_hi:[0,1]
	v_pk_mul_f32 v[6:7], v[196:197], v[6:7] op_sel_hi:[0,1]
	v_pk_mul_f32 v[2:3], v[196:197], v[8:9] op_sel_hi:[0,1]
	s_addk_i32 s0, 0x80
	v_mov_b32_e32 v16, 1.0
	v_cvt_pk_bf16_f32 v0, v0, v1
	v_cvt_pk_bf16_f32 v1, v10, v11
	v_cvt_pk_bf16_f32 v2, v2, v3
	v_cvt_pk_bf16_f32 v3, v6, v7
	s_bfe_u32 s0, s0, 0x60006
	v_mov_b32_e32 v8, 0
	s_and_b64 vcc, exec, s[12:13]
	v_mov_b32_e32 v24, 0
	v_mov_b32_e32 v25, 0
	v_mov_b32_e32 v26, 0
	v_mov_b32_e32 v27, 0
	v_mov_b32_e32 v28, 1.0
	v_mov_b32_e32 v29, 1.0
	v_mov_b32_e32 v30, 1.0
	v_mov_b32_e32 v31, 1.0
	global_store_dwordx4 v[4:5], v[0:3], off offset:256 nt
	s_cbranch_vccnz .LBB0_531
	s_nop 0
	v_mov_b32_e32 v0, s0
	v_cndmask_b32_e64 v0, v204, v0, s[6:7]
	v_lshlrev_b32_e32 v32, 6, v0
	v_lshl_add_u64 v[0:1], v[192:193], 0, v[32:33]
	v_lshl_add_u64 v[2:3], v[194:195], 0, v[32:33]
	global_load_dwordx4 v[28:31], v[0:1], off
	global_load_dwordx4 v[24:27], v[2:3], off
